# write-through (sc1) 16-byte stores in GEMM epilogues and norm X stores: less dirty L2 for the grid-barrier release to flush
# speedup vs baseline: 1.0234x; 1.0193x over previous
.LBB0_98:
	s_add_u32 s4, s44, 0xfffc0080
	s_addc_u32 s5, s45, -1
	s_add_i32 s12, 0, 0x10000
	v_add_u32_e32 v140, s12, v143
	ds_read_b128 v[146:149], v140
	ds_read_b128 v[150:153], v140 offset:1024
	ds_read_b128 v[154:157], v140 offset:2048
	ds_read_b128 v[158:161], v140 offset:3072
	s_cmp_eq_u32 s55, 12
	s_cselect_b32 s49, s23, s5
	s_cselect_b32 s48, s51, s4
	s_cselect_b32 s47, s25, s54
	s_cselect_b32 s46, s52, s53
	v_lshl_add_u64 v[140:141], s[44:45], 0, v[136:137]
	s_add_i32 m0, s11, 0xc000
	ds_read_b128 v[162:165], v145
	ds_read_b128 v[166:169], v145 offset:1024
	ds_read_b128 v[176:179], v145 offset:2048
	ds_read_b128 v[180:183], v145 offset:3072
	ds_read_b128 v[184:187], v145 offset:4096
	ds_read_b128 v[188:191], v145 offset:5120
	ds_read_b128 v[192:195], v145 offset:6144
	ds_read_b128 v[196:199], v145 offset:7168
	global_load_lds_dwordx4 v[140:141], off
	v_lshl_add_u64 v[140:141], s[44:45], 0, v[138:139]
	s_add_i32 m0, s11, 0xe000
	s_nop 0
	global_load_lds_dwordx4 v[140:141], off
	s_waitcnt lgkmcnt(8)
	s_barrier
	s_waitcnt lgkmcnt(0)
	s_setprio 1
	s_waitcnt lgkmcnt(0)
	v_mfma_f32_16x16x32_bf16 v[126:129], v[146:149], v[162:165], v[126:129]
	v_mfma_f32_16x16x32_bf16 v[118:121], v[154:157], v[162:165], v[118:121]
	v_mfma_f32_16x16x32_bf16 v[110:113], v[146:149], v[176:179], v[110:113]
	v_mfma_f32_16x16x32_bf16 v[102:105], v[154:157], v[176:179], v[102:105]
	v_mfma_f32_16x16x32_bf16 v[94:97], v[146:149], v[184:187], v[94:97]
	v_mfma_f32_16x16x32_bf16 v[86:89], v[154:157], v[184:187], v[86:89]
	v_mfma_f32_16x16x32_bf16 v[78:81], v[146:149], v[192:195], v[78:81]
	v_mfma_f32_16x16x32_bf16 v[70:73], v[154:157], v[192:195], v[70:73]
	v_mfma_f32_16x16x32_bf16 v[126:129], v[150:153], v[166:169], v[126:129]
	v_mfma_f32_16x16x32_bf16 v[118:121], v[158:161], v[166:169], v[118:121]
	v_mfma_f32_16x16x32_bf16 v[110:113], v[150:153], v[180:183], v[110:113]
	v_mfma_f32_16x16x32_bf16 v[102:105], v[158:161], v[180:183], v[102:105]
	v_mfma_f32_16x16x32_bf16 v[94:97], v[150:153], v[188:191], v[94:97]
	v_mfma_f32_16x16x32_bf16 v[86:89], v[158:161], v[188:191], v[86:89]
	v_mfma_f32_16x16x32_bf16 v[78:81], v[150:153], v[196:199], v[78:81]
	v_mfma_f32_16x16x32_bf16 v[70:73], v[158:161], v[196:199], v[70:73]
	s_setprio 0
	s_barrier
	s_add_i32 s13, 0, 0x14000
	v_add_u32_e32 v140, s13, v143
	s_add_i32 s4, s12, s6
	ds_read_b128 v[228:231], v140
	ds_read_b128 v[232:235], v140 offset:1024
	ds_read_b128 v[236:239], v140 offset:2048
	ds_read_b128 v[240:243], v140 offset:3072
	v_lshl_add_u64 v[140:141], s[46:47], 0, v[0:1]
	s_mov_b32 m0, s4
	v_lshl_add_u64 v[200:201], s[46:47], 0, v[130:131]
	global_load_lds_dwordx4 v[140:141], off
	s_add_i32 m0, s4, 0x2000
	s_nop 0
	global_load_lds_dwordx4 v[200:201], off
	s_barrier
	s_waitcnt lgkmcnt(0)
	s_setprio 1
	s_waitcnt lgkmcnt(0)
	v_mfma_f32_16x16x32_bf16 v[122:125], v[228:231], v[162:165], v[122:125]
	v_mfma_f32_16x16x32_bf16 v[114:117], v[236:239], v[162:165], v[114:117]
	v_mfma_f32_16x16x32_bf16 v[106:109], v[228:231], v[176:179], v[106:109]
	v_mfma_f32_16x16x32_bf16 v[98:101], v[236:239], v[176:179], v[98:101]
	v_mfma_f32_16x16x32_bf16 v[90:93], v[228:231], v[184:187], v[90:93]
	v_mfma_f32_16x16x32_bf16 v[82:85], v[236:239], v[184:187], v[82:85]
	v_mfma_f32_16x16x32_bf16 v[74:77], v[228:231], v[192:195], v[74:77]
	v_mfma_f32_16x16x32_bf16 v[66:69], v[236:239], v[192:195], v[66:69]
	v_mfma_f32_16x16x32_bf16 v[122:125], v[232:235], v[166:169], v[122:125]
	v_mfma_f32_16x16x32_bf16 v[114:117], v[240:243], v[166:169], v[114:117]
	v_mfma_f32_16x16x32_bf16 v[106:109], v[232:235], v[180:183], v[106:109]
	v_mfma_f32_16x16x32_bf16 v[98:101], v[240:243], v[180:183], v[98:101]
	v_mfma_f32_16x16x32_bf16 v[90:93], v[232:235], v[188:191], v[90:93]
	v_mfma_f32_16x16x32_bf16 v[82:85], v[240:243], v[188:191], v[82:85]
	v_mfma_f32_16x16x32_bf16 v[74:77], v[232:235], v[196:199], v[74:77]
	v_mfma_f32_16x16x32_bf16 v[66:69], v[240:243], v[196:199], v[66:69]
	s_setprio 0
	s_mov_b32 m0, s11
	v_lshl_add_u64 v[244:245], s[48:49], 0, v[134:135]
	s_barrier
	ds_read_b128 v[162:165], v145 offset:16384
	ds_read_b128 v[166:169], v145 offset:17408
	ds_read_b128 v[176:179], v145 offset:18432
	ds_read_b128 v[180:183], v145 offset:19456
	ds_read_b128 v[184:187], v145 offset:20480
	ds_read_b128 v[188:191], v145 offset:21504
	ds_read_b128 v[192:195], v145 offset:22528
	ds_read_b128 v[196:199], v145 offset:23552
	global_load_lds_dwordx4 v[244:245], off
	v_lshl_add_u64 v[246:247], s[48:49], 0, v[132:133]
	s_mov_b32 m0, s14
	s_nop 0
	global_load_lds_dwordx4 v[246:247], off
	s_barrier
	s_waitcnt lgkmcnt(0)
	s_setprio 1
	s_waitcnt lgkmcnt(0)
	v_mfma_f32_16x16x32_bf16 v[62:65], v[146:149], v[162:165], v[62:65]
	v_mfma_f32_16x16x32_bf16 v[54:57], v[154:157], v[162:165], v[54:57]
	v_mfma_f32_16x16x32_bf16 v[46:49], v[146:149], v[176:179], v[46:49]
	v_mfma_f32_16x16x32_bf16 v[38:41], v[154:157], v[176:179], v[38:41]
	v_mfma_f32_16x16x32_bf16 v[30:33], v[146:149], v[184:187], v[30:33]
	v_mfma_f32_16x16x32_bf16 v[22:25], v[154:157], v[184:187], v[22:25]
	v_mfma_f32_16x16x32_bf16 v[14:17], v[146:149], v[192:195], v[14:17]
	v_mfma_f32_16x16x32_bf16 v[6:9], v[154:157], v[192:195], v[6:9]
	v_mfma_f32_16x16x32_bf16 v[62:65], v[150:153], v[166:169], v[62:65]
	v_mfma_f32_16x16x32_bf16 v[54:57], v[158:161], v[166:169], v[54:57]
	v_mfma_f32_16x16x32_bf16 v[46:49], v[150:153], v[180:183], v[46:49]
	v_mfma_f32_16x16x32_bf16 v[38:41], v[158:161], v[180:183], v[38:41]
	v_mfma_f32_16x16x32_bf16 v[30:33], v[150:153], v[188:191], v[30:33]
	v_mfma_f32_16x16x32_bf16 v[22:25], v[158:161], v[188:191], v[22:25]
	v_mfma_f32_16x16x32_bf16 v[14:17], v[150:153], v[196:199], v[14:17]
	v_mfma_f32_16x16x32_bf16 v[6:9], v[158:161], v[196:199], v[6:9]
	s_setprio 0
	s_barrier
	s_add_u32 s4, s46, 0x40000
	s_addc_u32 s5, s47, 0
	s_add_i32 s12, s13, s6
	v_lshl_add_u64 v[146:147], s[4:5], 0, v[0:1]
	s_mov_b32 m0, s12
	s_nop 0
	global_load_lds_dwordx4 v[146:147], off
	v_lshl_add_u64 v[146:147], s[4:5], 0, v[130:131]
	s_add_i32 m0, s12, 0x2000
	s_nop 0
	global_load_lds_dwordx4 v[146:147], off
	s_waitcnt vmcnt(6)
	s_barrier
	s_setprio 1
	v_mfma_f32_16x16x32_bf16 v[58:61], v[228:231], v[162:165], v[58:61]
	v_mfma_f32_16x16x32_bf16 v[50:53], v[236:239], v[162:165], v[50:53]
	v_mfma_f32_16x16x32_bf16 v[42:45], v[228:231], v[176:179], v[42:45]
	v_mfma_f32_16x16x32_bf16 v[34:37], v[236:239], v[176:179], v[34:37]
	v_mfma_f32_16x16x32_bf16 v[26:29], v[228:231], v[184:187], v[26:29]
	v_mfma_f32_16x16x32_bf16 v[18:21], v[236:239], v[184:187], v[18:21]
	v_mfma_f32_16x16x32_bf16 v[10:13], v[228:231], v[192:195], v[10:13]
	v_mfma_f32_16x16x32_bf16 v[2:5], v[236:239], v[192:195], v[2:5]
	v_mfma_f32_16x16x32_bf16 v[58:61], v[232:235], v[166:169], v[58:61]
	v_mfma_f32_16x16x32_bf16 v[50:53], v[240:243], v[166:169], v[50:53]
	v_mfma_f32_16x16x32_bf16 v[42:45], v[232:235], v[180:183], v[42:45]
	v_mfma_f32_16x16x32_bf16 v[34:37], v[240:243], v[180:183], v[34:37]
	v_mfma_f32_16x16x32_bf16 v[26:29], v[232:235], v[188:191], v[26:29]
	v_mfma_f32_16x16x32_bf16 v[18:21], v[240:243], v[188:191], v[18:21]
	v_mfma_f32_16x16x32_bf16 v[10:13], v[232:235], v[196:199], v[10:13]
	v_mfma_f32_16x16x32_bf16 v[2:5], v[240:243], v[196:199], v[2:5]
	s_setprio 0
	s_add_i32 s12, 0, 0x18000
	v_add_u32_e32 v158, s12, v143
	s_barrier
	ds_read_b128 v[146:149], v158
	ds_read_b128 v[150:153], v158 offset:1024
	ds_read_b128 v[154:157], v158 offset:2048
	ds_read_b128 v[158:161], v158 offset:3072
	s_add_u32 s4, s48, 0x40000
	s_addc_u32 s5, s49, 0
	s_mov_b32 m0, s15
	v_lshl_add_u64 v[228:229], s[4:5], 0, v[134:135]
	ds_read_b128 v[162:165], v145 offset:32768
	ds_read_b128 v[166:169], v145 offset:33792
	ds_read_b128 v[176:179], v145 offset:34816
	ds_read_b128 v[180:183], v145 offset:35840
	ds_read_b128 v[184:187], v145 offset:36864
	ds_read_b128 v[188:191], v145 offset:37888
	ds_read_b128 v[192:195], v145 offset:38912
	ds_read_b128 v[196:199], v145 offset:39936
	global_load_lds_dwordx4 v[228:229], off
	v_lshl_add_u64 v[228:229], s[4:5], 0, v[132:133]
	s_mov_b32 m0, s18
	s_nop 0
	global_load_lds_dwordx4 v[228:229], off
	s_waitcnt lgkmcnt(8)
	s_barrier
	s_waitcnt lgkmcnt(0)
	s_setprio 1
	s_waitcnt lgkmcnt(0)
	v_mfma_f32_16x16x32_bf16 v[126:129], v[146:149], v[162:165], v[126:129]
	v_mfma_f32_16x16x32_bf16 v[118:121], v[154:157], v[162:165], v[118:121]
	v_mfma_f32_16x16x32_bf16 v[110:113], v[146:149], v[176:179], v[110:113]
	v_mfma_f32_16x16x32_bf16 v[102:105], v[154:157], v[176:179], v[102:105]
	v_mfma_f32_16x16x32_bf16 v[94:97], v[146:149], v[184:187], v[94:97]
	v_mfma_f32_16x16x32_bf16 v[86:89], v[154:157], v[184:187], v[86:89]
	v_mfma_f32_16x16x32_bf16 v[78:81], v[146:149], v[192:195], v[78:81]
	v_mfma_f32_16x16x32_bf16 v[70:73], v[154:157], v[192:195], v[70:73]
	v_mfma_f32_16x16x32_bf16 v[126:129], v[150:153], v[166:169], v[126:129]
	v_mfma_f32_16x16x32_bf16 v[118:121], v[158:161], v[166:169], v[118:121]
	v_mfma_f32_16x16x32_bf16 v[110:113], v[150:153], v[180:183], v[110:113]
	v_mfma_f32_16x16x32_bf16 v[102:105], v[158:161], v[180:183], v[102:105]
	v_mfma_f32_16x16x32_bf16 v[94:97], v[150:153], v[188:191], v[94:97]
	v_mfma_f32_16x16x32_bf16 v[86:89], v[158:161], v[188:191], v[86:89]
	v_mfma_f32_16x16x32_bf16 v[78:81], v[150:153], v[196:199], v[78:81]
	v_mfma_f32_16x16x32_bf16 v[70:73], v[158:161], v[196:199], v[70:73]
	s_setprio 0
	s_barrier
	s_add_i32 s13, 0, 0x1c000
	s_add_i32 s4, s12, s6
	v_add_u32_e32 v175, s13, v143
	v_lshl_add_u64 v[140:141], v[140:141], 0, s[34:35]
	s_mov_b32 m0, s4
	ds_read_b128 v[228:231], v175
	ds_read_b128 v[232:235], v175 offset:1024
	ds_read_b128 v[236:239], v175 offset:2048
	ds_read_b128 v[240:243], v175 offset:3072
	global_load_lds_dwordx4 v[140:141], off
	v_lshl_add_u64 v[140:141], v[200:201], 0, s[34:35]
	s_add_i32 m0, s4, 0x2000
	s_nop 0
	global_load_lds_dwordx4 v[140:141], off
	s_barrier
	s_waitcnt lgkmcnt(0)
	s_setprio 1
	s_waitcnt lgkmcnt(0)
	v_mfma_f32_16x16x32_bf16 v[122:125], v[228:231], v[162:165], v[122:125]
	v_mfma_f32_16x16x32_bf16 v[114:117], v[236:239], v[162:165], v[114:117]
	v_mfma_f32_16x16x32_bf16 v[106:109], v[228:231], v[176:179], v[106:109]
	v_mfma_f32_16x16x32_bf16 v[98:101], v[236:239], v[176:179], v[98:101]
	v_mfma_f32_16x16x32_bf16 v[90:93], v[228:231], v[184:187], v[90:93]
	v_mfma_f32_16x16x32_bf16 v[82:85], v[236:239], v[184:187], v[82:85]
	v_mfma_f32_16x16x32_bf16 v[74:77], v[228:231], v[192:195], v[74:77]
	v_mfma_f32_16x16x32_bf16 v[66:69], v[236:239], v[192:195], v[66:69]
	v_mfma_f32_16x16x32_bf16 v[122:125], v[232:235], v[166:169], v[122:125]
	v_mfma_f32_16x16x32_bf16 v[114:117], v[240:243], v[166:169], v[114:117]
	v_mfma_f32_16x16x32_bf16 v[106:109], v[232:235], v[180:183], v[106:109]
	v_mfma_f32_16x16x32_bf16 v[98:101], v[240:243], v[180:183], v[98:101]
	v_mfma_f32_16x16x32_bf16 v[90:93], v[232:235], v[188:191], v[90:93]
	v_mfma_f32_16x16x32_bf16 v[82:85], v[240:243], v[188:191], v[82:85]
	v_mfma_f32_16x16x32_bf16 v[74:77], v[232:235], v[196:199], v[74:77]
	v_mfma_f32_16x16x32_bf16 v[66:69], v[240:243], v[196:199], v[66:69]
	s_setprio 0
	s_mov_b32 m0, s20
	v_lshl_add_u64 v[140:141], v[244:245], 0, s[34:35]
	s_barrier
	ds_read_b128 v[162:165], v145 offset:49152
	ds_read_b128 v[166:169], v145 offset:50176
	ds_read_b128 v[176:179], v145 offset:51200
	ds_read_b128 v[180:183], v145 offset:52224
	ds_read_b128 v[184:187], v145 offset:53248
	ds_read_b128 v[188:191], v145 offset:54272
	ds_read_b128 v[192:195], v145 offset:55296
	ds_read_b128 v[196:199], v145 offset:56320
	global_load_lds_dwordx4 v[140:141], off
	v_lshl_add_u64 v[140:141], v[246:247], 0, s[34:35]
	s_mov_b32 m0, s21
	s_nop 0
	global_load_lds_dwordx4 v[140:141], off
	s_barrier
	s_waitcnt lgkmcnt(0)
	s_setprio 1
	s_waitcnt lgkmcnt(0)
	v_mfma_f32_16x16x32_bf16 v[62:65], v[146:149], v[162:165], v[62:65]
	v_mfma_f32_16x16x32_bf16 v[54:57], v[154:157], v[162:165], v[54:57]
	v_mfma_f32_16x16x32_bf16 v[46:49], v[146:149], v[176:179], v[46:49]
	v_mfma_f32_16x16x32_bf16 v[38:41], v[154:157], v[176:179], v[38:41]
	v_mfma_f32_16x16x32_bf16 v[30:33], v[146:149], v[184:187], v[30:33]
	v_mfma_f32_16x16x32_bf16 v[22:25], v[154:157], v[184:187], v[22:25]
	v_mfma_f32_16x16x32_bf16 v[14:17], v[146:149], v[192:195], v[14:17]
	v_mfma_f32_16x16x32_bf16 v[6:9], v[154:157], v[192:195], v[6:9]
	v_mfma_f32_16x16x32_bf16 v[62:65], v[150:153], v[166:169], v[62:65]
	v_mfma_f32_16x16x32_bf16 v[54:57], v[158:161], v[166:169], v[54:57]
	v_mfma_f32_16x16x32_bf16 v[46:49], v[150:153], v[180:183], v[46:49]
	v_mfma_f32_16x16x32_bf16 v[38:41], v[158:161], v[180:183], v[38:41]
	v_mfma_f32_16x16x32_bf16 v[30:33], v[150:153], v[188:191], v[30:33]
	v_mfma_f32_16x16x32_bf16 v[22:25], v[158:161], v[188:191], v[22:25]
	v_mfma_f32_16x16x32_bf16 v[14:17], v[150:153], v[196:199], v[14:17]
	v_mfma_f32_16x16x32_bf16 v[6:9], v[158:161], v[196:199], v[6:9]
	s_setprio 0
	s_barrier
	s_add_u32 s4, s46, 0x40080
	s_addc_u32 s5, s47, 0
	s_add_i32 s12, s13, s6
	v_lshl_add_u64 v[140:141], s[4:5], 0, v[0:1]
	s_mov_b32 m0, s12
	s_nop 0
	global_load_lds_dwordx4 v[140:141], off
	v_lshl_add_u64 v[140:141], s[4:5], 0, v[130:131]
	s_add_i32 m0, s12, 0x2000
	s_nop 0
	global_load_lds_dwordx4 v[140:141], off
	s_waitcnt vmcnt(6)
	s_barrier
	s_setprio 1
	v_mfma_f32_16x16x32_bf16 v[58:61], v[228:231], v[162:165], v[58:61]
	v_mfma_f32_16x16x32_bf16 v[50:53], v[236:239], v[162:165], v[50:53]
	v_mfma_f32_16x16x32_bf16 v[42:45], v[228:231], v[176:179], v[42:45]
	v_mfma_f32_16x16x32_bf16 v[34:37], v[236:239], v[176:179], v[34:37]
	v_mfma_f32_16x16x32_bf16 v[26:29], v[228:231], v[184:187], v[26:29]
	v_mfma_f32_16x16x32_bf16 v[18:21], v[236:239], v[184:187], v[18:21]
	v_mfma_f32_16x16x32_bf16 v[10:13], v[228:231], v[192:195], v[10:13]
	v_mfma_f32_16x16x32_bf16 v[2:5], v[236:239], v[192:195], v[2:5]
	v_mfma_f32_16x16x32_bf16 v[58:61], v[232:235], v[166:169], v[58:61]
	v_mfma_f32_16x16x32_bf16 v[50:53], v[240:243], v[166:169], v[50:53]
	v_mfma_f32_16x16x32_bf16 v[42:45], v[232:235], v[180:183], v[42:45]
	v_mfma_f32_16x16x32_bf16 v[34:37], v[240:243], v[180:183], v[34:37]
	v_mfma_f32_16x16x32_bf16 v[26:29], v[232:235], v[188:191], v[26:29]
	v_mfma_f32_16x16x32_bf16 v[18:21], v[240:243], v[188:191], v[18:21]
	v_mfma_f32_16x16x32_bf16 v[10:13], v[232:235], v[196:199], v[10:13]
	v_mfma_f32_16x16x32_bf16 v[2:5], v[240:243], v[196:199], v[2:5]
	s_setprio 0
	s_add_i32 s55, s55, 2
	s_add_u32 s44, s44, 0x100
	s_addc_u32 s45, s45, 0
	s_add_u32 s53, s53, 0x100
	s_addc_u32 s54, s54, 0
	s_cmp_gt_u32 s55, 13
	s_barrier
	s_cbranch_scc0 .LBB0_98
	v_mul_f32_e32 v147, 0xbfb8aa3b, v126
	v_exp_f32_e32 v147, v147
	v_readlane_b32 s4, v254, 0
	v_lshl_or_b32 v148, s50, 7, v144
	v_readlane_b32 s5, v254, 1
	v_add_f32_e32 v147, 1.0, v147
	v_rcp_f32_e32 v152, v147
	v_mul_f32_e32 v147, 0xbfb8aa3b, v127
	v_exp_f32_e32 v147, v147
	v_lshl_add_u32 v146, s33, 8, v142
	v_ashrrev_i32_e32 v149, 31, v148
	v_mov_b64_e32 v[140:141], s[4:5]
	v_add_f32_e32 v147, 1.0, v147
	v_rcp_f32_e32 v153, v147
	s_movk_i32 s12, 0x1600
	v_mad_i64_i32 v[150:151], s[4:5], v146, s12, v[140:141]
	v_pk_mul_f32 v[126:127], v[126:127], v[152:153]
	s_and_b64 vcc, exec, s[40:41]
	v_pk_mul_f32 v[122:123], v[126:127], v[122:123]
	v_mul_f32_e32 v126, 0xbfb8aa3b, v128
	v_mul_f32_e32 v127, 0xbfb8aa3b, v129
	v_exp_f32_e32 v126, v126
	v_exp_f32_e32 v127, v127
	s_mov_b32 s50, s24
	s_mov_b32 s33, s22
	v_add_f32_e32 v126, 1.0, v126
	v_add_f32_e32 v127, 1.0, v127
	v_rcp_f32_e32 v126, v126
	v_rcp_f32_e32 v127, v127
	s_mov_b64 s[46:47], s[42:43]
	s_mov_b64 s[44:45], s[38:39]
	v_pk_mul_f32 v[126:127], v[128:129], v[126:127]
	s_nop 0
	v_pk_mul_f32 v[124:125], v[126:127], v[124:125]
	v_mul_f32_e32 v126, 0xbfb8aa3b, v118
	v_mul_f32_e32 v127, 0xbfb8aa3b, v119
	v_exp_f32_e32 v126, v126
	v_exp_f32_e32 v127, v127
	v_add_f32_e32 v126, 1.0, v126
	v_add_f32_e32 v127, 1.0, v127
	v_rcp_f32_e32 v126, v126
	v_rcp_f32_e32 v127, v127
	s_nop 0
	v_pk_mul_f32 v[118:119], v[118:119], v[126:127]
	s_nop 0
	v_pk_mul_f32 v[118:119], v[118:119], v[114:115]
	v_mul_f32_e32 v114, 0xbfb8aa3b, v120
	v_mul_f32_e32 v115, 0xbfb8aa3b, v121
	v_exp_f32_e32 v114, v114
	v_exp_f32_e32 v115, v115
	v_cvt_pk_bf16_f32 v118, v118, v119
	v_add_f32_e32 v114, 1.0, v114
	v_add_f32_e32 v115, 1.0, v115
	v_rcp_f32_e32 v114, v114
	v_rcp_f32_e32 v115, v115
	s_nop 0
	v_pk_mul_f32 v[114:115], v[120:121], v[114:115]
	s_nop 0
	v_pk_mul_f32 v[120:121], v[114:115], v[116:117]
	v_lshlrev_b64 v[114:115], 1, v[148:149]
	v_lshl_add_u64 v[126:127], v[150:151], 0, v[114:115]
	v_cvt_pk_bf16_f32 v116, v122, v123
	v_cvt_pk_bf16_f32 v117, v124, v125
	v_cvt_pk_bf16_f32 v119, v120, v121
	global_store_dwordx4 v[126:127], v[116:119], off sc1
	s_nop 1
	v_mul_f32_e32 v118, 0xbfb8aa3b, v110
	v_mul_f32_e32 v119, 0xbfb8aa3b, v111
	v_exp_f32_e32 v118, v118
	v_exp_f32_e32 v119, v119
	v_or_b32_e32 v116, 16, v146
	v_mad_i64_i32 v[116:117], s[4:5], v116, s12, v[140:141]
	v_add_f32_e32 v118, 1.0, v118
	v_add_f32_e32 v119, 1.0, v119
	v_rcp_f32_e32 v118, v118
	v_rcp_f32_e32 v119, v119
	s_nop 0
	v_pk_mul_f32 v[110:111], v[110:111], v[118:119]
	s_nop 0
	v_pk_mul_f32 v[106:107], v[110:111], v[106:107]
	v_mul_f32_e32 v110, 0xbfb8aa3b, v112
	v_mul_f32_e32 v111, 0xbfb8aa3b, v113
	v_exp_f32_e32 v110, v110
	v_exp_f32_e32 v111, v111
	v_add_f32_e32 v110, 1.0, v110
	v_add_f32_e32 v111, 1.0, v111
	v_rcp_f32_e32 v110, v110
	v_rcp_f32_e32 v111, v111
	s_nop 0
	v_pk_mul_f32 v[110:111], v[112:113], v[110:111]
	s_nop 0
	v_pk_mul_f32 v[108:109], v[110:111], v[108:109]
	v_mul_f32_e32 v110, 0xbfb8aa3b, v102
	v_mul_f32_e32 v111, 0xbfb8aa3b, v103
	v_exp_f32_e32 v110, v110
	v_exp_f32_e32 v111, v111
	v_add_f32_e32 v110, 1.0, v110
	v_add_f32_e32 v111, 1.0, v111
	v_rcp_f32_e32 v110, v110
	v_rcp_f32_e32 v111, v111
	s_nop 0
	v_pk_mul_f32 v[102:103], v[102:103], v[110:111]
	s_nop 0
	v_pk_mul_f32 v[102:103], v[102:103], v[98:99]
	v_mul_f32_e32 v98, 0xbfb8aa3b, v104
	v_mul_f32_e32 v99, 0xbfb8aa3b, v105
	v_exp_f32_e32 v98, v98
	v_exp_f32_e32 v99, v99
	v_lshl_add_u64 v[110:111], v[116:117], 0, v[114:115]
	v_add_f32_e32 v98, 1.0, v98
	v_add_f32_e32 v99, 1.0, v99
	v_rcp_f32_e32 v98, v98
	v_rcp_f32_e32 v99, v99
	s_nop 0
	v_pk_mul_f32 v[98:99], v[104:105], v[98:99]
	s_nop 0
	v_pk_mul_f32 v[104:105], v[98:99], v[100:101]
	v_cvt_pk_bf16_f32 v98, v106, v107
	v_cvt_pk_bf16_f32 v99, v108, v109
	v_cvt_pk_bf16_f32 v100, v102, v103
	v_cvt_pk_bf16_f32 v101, v104, v105
	global_store_dwordx4 v[110:111], v[98:101], off sc1
	s_nop 1
	v_mul_f32_e32 v100, 0xbfb8aa3b, v94
	v_mul_f32_e32 v101, 0xbfb8aa3b, v95
	v_exp_f32_e32 v100, v100
	v_exp_f32_e32 v101, v101
	v_or_b32_e32 v98, 32, v146
	v_mad_i64_i32 v[98:99], s[4:5], v98, s12, v[140:141]
	v_add_f32_e32 v100, 1.0, v100
	v_add_f32_e32 v101, 1.0, v101
	v_rcp_f32_e32 v100, v100
	v_rcp_f32_e32 v101, v101
	s_nop 0
	v_pk_mul_f32 v[94:95], v[94:95], v[100:101]
	s_nop 0
	v_pk_mul_f32 v[90:91], v[94:95], v[90:91]
	v_mul_f32_e32 v94, 0xbfb8aa3b, v96
	v_mul_f32_e32 v95, 0xbfb8aa3b, v97
	v_exp_f32_e32 v94, v94
	v_exp_f32_e32 v95, v95
	v_add_f32_e32 v94, 1.0, v94
	v_add_f32_e32 v95, 1.0, v95
	v_rcp_f32_e32 v94, v94
	v_rcp_f32_e32 v95, v95
	s_nop 0
	v_pk_mul_f32 v[94:95], v[96:97], v[94:95]
	s_nop 0
	v_pk_mul_f32 v[92:93], v[94:95], v[92:93]
	v_mul_f32_e32 v94, 0xbfb8aa3b, v86
	v_mul_f32_e32 v95, 0xbfb8aa3b, v87
	v_exp_f32_e32 v94, v94
	v_exp_f32_e32 v95, v95
	v_add_f32_e32 v94, 1.0, v94
	v_add_f32_e32 v95, 1.0, v95
	v_rcp_f32_e32 v94, v94
	v_rcp_f32_e32 v95, v95
	s_nop 0
	v_pk_mul_f32 v[86:87], v[86:87], v[94:95]
	s_nop 0
	v_pk_mul_f32 v[86:87], v[86:87], v[82:83]
	v_mul_f32_e32 v82, 0xbfb8aa3b, v88
	v_mul_f32_e32 v83, 0xbfb8aa3b, v89
	v_exp_f32_e32 v82, v82
	v_exp_f32_e32 v83, v83
	v_lshl_add_u64 v[94:95], v[98:99], 0, v[114:115]
	v_add_f32_e32 v82, 1.0, v82
	v_add_f32_e32 v83, 1.0, v83
	v_rcp_f32_e32 v82, v82
	v_rcp_f32_e32 v83, v83
	s_nop 0
	v_pk_mul_f32 v[82:83], v[88:89], v[82:83]
	s_nop 0
	v_pk_mul_f32 v[88:89], v[82:83], v[84:85]
	v_cvt_pk_bf16_f32 v82, v90, v91
	v_cvt_pk_bf16_f32 v83, v92, v93
	v_cvt_pk_bf16_f32 v84, v86, v87
	v_cvt_pk_bf16_f32 v85, v88, v89
	global_store_dwordx4 v[94:95], v[82:85], off sc1
	s_nop 1
	v_mul_f32_e32 v84, 0xbfb8aa3b, v78
	v_mul_f32_e32 v85, 0xbfb8aa3b, v79
	v_exp_f32_e32 v84, v84
	v_exp_f32_e32 v85, v85
	v_or_b32_e32 v82, 48, v146
	v_mad_i64_i32 v[82:83], s[4:5], v82, s12, v[140:141]
	v_add_f32_e32 v84, 1.0, v84
	v_add_f32_e32 v85, 1.0, v85
	v_rcp_f32_e32 v84, v84
	v_rcp_f32_e32 v85, v85
	s_nop 0
	v_pk_mul_f32 v[78:79], v[78:79], v[84:85]
	s_nop 0
	v_pk_mul_f32 v[74:75], v[78:79], v[74:75]
	v_mul_f32_e32 v78, 0xbfb8aa3b, v80
	v_mul_f32_e32 v79, 0xbfb8aa3b, v81
	v_exp_f32_e32 v78, v78
	v_exp_f32_e32 v79, v79
	v_add_f32_e32 v78, 1.0, v78
	v_add_f32_e32 v79, 1.0, v79
	v_rcp_f32_e32 v78, v78
	v_rcp_f32_e32 v79, v79
	s_nop 0
	v_pk_mul_f32 v[78:79], v[80:81], v[78:79]
	s_nop 0
	v_pk_mul_f32 v[76:77], v[78:79], v[76:77]
	v_mul_f32_e32 v78, 0xbfb8aa3b, v70
	v_mul_f32_e32 v79, 0xbfb8aa3b, v71
	v_exp_f32_e32 v78, v78
	v_exp_f32_e32 v79, v79
	v_add_f32_e32 v78, 1.0, v78
	v_add_f32_e32 v79, 1.0, v79
	v_rcp_f32_e32 v78, v78
	v_rcp_f32_e32 v79, v79
	s_nop 0
	v_pk_mul_f32 v[70:71], v[70:71], v[78:79]
	s_nop 0
	v_pk_mul_f32 v[70:71], v[70:71], v[66:67]
	v_mul_f32_e32 v66, 0xbfb8aa3b, v72
	v_mul_f32_e32 v67, 0xbfb8aa3b, v73
	v_exp_f32_e32 v66, v66
	v_exp_f32_e32 v67, v67
	v_lshl_add_u64 v[78:79], v[82:83], 0, v[114:115]
	v_add_f32_e32 v66, 1.0, v66
	v_add_f32_e32 v67, 1.0, v67
	v_rcp_f32_e32 v66, v66
	v_rcp_f32_e32 v67, v67
	s_nop 0
	v_pk_mul_f32 v[66:67], v[72:73], v[66:67]
	s_nop 0
	v_pk_mul_f32 v[72:73], v[66:67], v[68:69]
	v_cvt_pk_bf16_f32 v66, v74, v75
	v_cvt_pk_bf16_f32 v67, v76, v77
	v_cvt_pk_bf16_f32 v68, v70, v71
	v_cvt_pk_bf16_f32 v69, v72, v73
	global_store_dwordx4 v[78:79], v[66:69], off sc1
	s_nop 1
	v_mul_f32_e32 v68, 0xbfb8aa3b, v62
	v_mul_f32_e32 v69, 0xbfb8aa3b, v63
	v_exp_f32_e32 v68, v68
	v_exp_f32_e32 v69, v69
	v_add_u32_e32 v66, 0x80, v146
	v_mad_i64_i32 v[66:67], s[4:5], v66, s12, v[140:141]
	v_add_f32_e32 v68, 1.0, v68
	v_add_f32_e32 v69, 1.0, v69
	v_rcp_f32_e32 v68, v68
	v_rcp_f32_e32 v69, v69
	s_nop 0
	v_pk_mul_f32 v[62:63], v[62:63], v[68:69]
	s_nop 0
	v_pk_mul_f32 v[58:59], v[62:63], v[58:59]
	v_mul_f32_e32 v62, 0xbfb8aa3b, v64
	v_mul_f32_e32 v63, 0xbfb8aa3b, v65
	v_exp_f32_e32 v62, v62
	v_exp_f32_e32 v63, v63
	v_add_f32_e32 v62, 1.0, v62
	v_add_f32_e32 v63, 1.0, v63
	v_rcp_f32_e32 v62, v62
	v_rcp_f32_e32 v63, v63
	s_nop 0
	v_pk_mul_f32 v[62:63], v[64:65], v[62:63]
	s_nop 0
	v_pk_mul_f32 v[60:61], v[62:63], v[60:61]
	v_mul_f32_e32 v62, 0xbfb8aa3b, v54
	v_mul_f32_e32 v63, 0xbfb8aa3b, v55
	v_exp_f32_e32 v62, v62
	v_exp_f32_e32 v63, v63
	v_add_f32_e32 v62, 1.0, v62
	v_add_f32_e32 v63, 1.0, v63
	v_rcp_f32_e32 v62, v62
	v_rcp_f32_e32 v63, v63
	s_nop 0
	v_pk_mul_f32 v[54:55], v[54:55], v[62:63]
	s_nop 0
	v_pk_mul_f32 v[54:55], v[54:55], v[50:51]
	v_mul_f32_e32 v50, 0xbfb8aa3b, v56
	v_mul_f32_e32 v51, 0xbfb8aa3b, v57
	v_exp_f32_e32 v50, v50
	v_exp_f32_e32 v51, v51
	v_lshl_add_u64 v[62:63], v[66:67], 0, v[114:115]
	v_add_f32_e32 v50, 1.0, v50
	v_add_f32_e32 v51, 1.0, v51
	v_rcp_f32_e32 v50, v50
	v_rcp_f32_e32 v51, v51
	s_nop 0
	v_pk_mul_f32 v[50:51], v[56:57], v[50:51]
	s_nop 0
	v_pk_mul_f32 v[56:57], v[50:51], v[52:53]
	v_cvt_pk_bf16_f32 v50, v58, v59
	v_cvt_pk_bf16_f32 v51, v60, v61
	v_cvt_pk_bf16_f32 v52, v54, v55
	v_cvt_pk_bf16_f32 v53, v56, v57
	global_store_dwordx4 v[62:63], v[50:53], off sc1
	s_nop 1
	v_mul_f32_e32 v52, 0xbfb8aa3b, v46
	v_mul_f32_e32 v53, 0xbfb8aa3b, v47
	v_exp_f32_e32 v52, v52
	v_exp_f32_e32 v53, v53
	v_add_u32_e32 v50, 0x90, v146
	v_mad_i64_i32 v[50:51], s[4:5], v50, s12, v[140:141]
	v_add_f32_e32 v52, 1.0, v52
	v_add_f32_e32 v53, 1.0, v53
	v_rcp_f32_e32 v52, v52
	v_rcp_f32_e32 v53, v53
	s_nop 0
	v_pk_mul_f32 v[46:47], v[46:47], v[52:53]
	s_nop 0
	v_pk_mul_f32 v[42:43], v[46:47], v[42:43]
	v_mul_f32_e32 v46, 0xbfb8aa3b, v48
	v_mul_f32_e32 v47, 0xbfb8aa3b, v49
	v_exp_f32_e32 v46, v46
	v_exp_f32_e32 v47, v47
	v_add_f32_e32 v46, 1.0, v46
	v_add_f32_e32 v47, 1.0, v47
	v_rcp_f32_e32 v46, v46
	v_rcp_f32_e32 v47, v47
	s_nop 0
	v_pk_mul_f32 v[46:47], v[48:49], v[46:47]
	s_nop 0
	v_pk_mul_f32 v[44:45], v[46:47], v[44:45]
	v_mul_f32_e32 v46, 0xbfb8aa3b, v38
	v_mul_f32_e32 v47, 0xbfb8aa3b, v39
	v_exp_f32_e32 v46, v46
	v_exp_f32_e32 v47, v47
	v_add_f32_e32 v46, 1.0, v46
	v_add_f32_e32 v47, 1.0, v47
	v_rcp_f32_e32 v46, v46
	v_rcp_f32_e32 v47, v47
	s_nop 0
	v_pk_mul_f32 v[38:39], v[38:39], v[46:47]
	s_nop 0
	v_pk_mul_f32 v[38:39], v[38:39], v[34:35]
	v_mul_f32_e32 v34, 0xbfb8aa3b, v40
	v_mul_f32_e32 v35, 0xbfb8aa3b, v41
	v_exp_f32_e32 v34, v34
	v_exp_f32_e32 v35, v35
	v_lshl_add_u64 v[46:47], v[50:51], 0, v[114:115]
	v_add_f32_e32 v34, 1.0, v34
	v_add_f32_e32 v35, 1.0, v35
	v_rcp_f32_e32 v34, v34
	v_rcp_f32_e32 v35, v35
	s_nop 0
	v_pk_mul_f32 v[34:35], v[40:41], v[34:35]
	s_nop 0
	v_pk_mul_f32 v[40:41], v[34:35], v[36:37]
	v_cvt_pk_bf16_f32 v34, v42, v43
	v_cvt_pk_bf16_f32 v35, v44, v45
	v_cvt_pk_bf16_f32 v36, v38, v39
	v_cvt_pk_bf16_f32 v37, v40, v41
	global_store_dwordx4 v[46:47], v[34:37], off sc1
	s_nop 1
	v_mul_f32_e32 v36, 0xbfb8aa3b, v30
	v_mul_f32_e32 v37, 0xbfb8aa3b, v31
	v_exp_f32_e32 v36, v36
	v_exp_f32_e32 v37, v37
	v_add_u32_e32 v34, 0xa0, v146
	v_mad_i64_i32 v[34:35], s[4:5], v34, s12, v[140:141]
	v_add_f32_e32 v36, 1.0, v36
	v_add_f32_e32 v37, 1.0, v37
	v_rcp_f32_e32 v36, v36
	v_rcp_f32_e32 v37, v37
	s_nop 0
	v_pk_mul_f32 v[30:31], v[30:31], v[36:37]
	s_nop 0
	v_pk_mul_f32 v[26:27], v[30:31], v[26:27]
	v_mul_f32_e32 v30, 0xbfb8aa3b, v32
	v_mul_f32_e32 v31, 0xbfb8aa3b, v33
	v_exp_f32_e32 v30, v30
	v_exp_f32_e32 v31, v31
	v_add_f32_e32 v30, 1.0, v30
	v_add_f32_e32 v31, 1.0, v31
	v_rcp_f32_e32 v30, v30
	v_rcp_f32_e32 v31, v31
	s_nop 0
	v_pk_mul_f32 v[30:31], v[32:33], v[30:31]
	s_nop 0
	v_pk_mul_f32 v[28:29], v[30:31], v[28:29]
	v_mul_f32_e32 v30, 0xbfb8aa3b, v22
	v_mul_f32_e32 v31, 0xbfb8aa3b, v23
	v_exp_f32_e32 v30, v30
	v_exp_f32_e32 v31, v31
	v_add_f32_e32 v30, 1.0, v30
	v_add_f32_e32 v31, 1.0, v31
	v_rcp_f32_e32 v30, v30
	v_rcp_f32_e32 v31, v31
	s_nop 0
	v_pk_mul_f32 v[22:23], v[22:23], v[30:31]
	s_nop 0
	v_pk_mul_f32 v[22:23], v[22:23], v[18:19]
	v_mul_f32_e32 v18, 0xbfb8aa3b, v24
	v_mul_f32_e32 v19, 0xbfb8aa3b, v25
	v_exp_f32_e32 v18, v18
	v_exp_f32_e32 v19, v19
	v_lshl_add_u64 v[30:31], v[34:35], 0, v[114:115]
	v_add_f32_e32 v18, 1.0, v18
	v_add_f32_e32 v19, 1.0, v19
	v_rcp_f32_e32 v18, v18
	v_rcp_f32_e32 v19, v19
	s_nop 0
	v_pk_mul_f32 v[18:19], v[24:25], v[18:19]
	s_nop 0
	v_pk_mul_f32 v[24:25], v[18:19], v[20:21]
	v_cvt_pk_bf16_f32 v18, v26, v27
	v_cvt_pk_bf16_f32 v19, v28, v29
	v_cvt_pk_bf16_f32 v20, v22, v23
	v_cvt_pk_bf16_f32 v21, v24, v25
	global_store_dwordx4 v[30:31], v[18:21], off sc1
	s_nop 1
	v_mul_f32_e32 v20, 0xbfb8aa3b, v14
	v_mul_f32_e32 v21, 0xbfb8aa3b, v15
	v_exp_f32_e32 v20, v20
	v_exp_f32_e32 v21, v21
	v_add_u32_e32 v18, 0xb0, v146
	v_mad_i64_i32 v[18:19], s[4:5], v18, s12, v[140:141]
	v_add_f32_e32 v20, 1.0, v20
	v_add_f32_e32 v21, 1.0, v21
	v_rcp_f32_e32 v20, v20
	v_rcp_f32_e32 v21, v21
	s_nop 0
	v_pk_mul_f32 v[14:15], v[14:15], v[20:21]
	s_nop 0
	v_pk_mul_f32 v[10:11], v[14:15], v[10:11]
	v_mul_f32_e32 v14, 0xbfb8aa3b, v16
	v_mul_f32_e32 v15, 0xbfb8aa3b, v17
	v_exp_f32_e32 v14, v14
	v_exp_f32_e32 v15, v15
	v_add_f32_e32 v14, 1.0, v14
	v_add_f32_e32 v15, 1.0, v15
	v_rcp_f32_e32 v14, v14
	v_rcp_f32_e32 v15, v15
	s_nop 0
	v_pk_mul_f32 v[14:15], v[16:17], v[14:15]
	s_nop 0
	v_pk_mul_f32 v[12:13], v[14:15], v[12:13]
	v_mul_f32_e32 v14, 0xbfb8aa3b, v6
	v_mul_f32_e32 v15, 0xbfb8aa3b, v7
	v_exp_f32_e32 v14, v14
	v_exp_f32_e32 v15, v15
	v_add_f32_e32 v14, 1.0, v14
	v_add_f32_e32 v15, 1.0, v15
	v_rcp_f32_e32 v14, v14
	v_rcp_f32_e32 v15, v15
	s_nop 0
	v_pk_mul_f32 v[6:7], v[6:7], v[14:15]
	s_nop 0
	v_pk_mul_f32 v[6:7], v[6:7], v[2:3]
	v_mul_f32_e32 v2, 0xbfb8aa3b, v8
	v_mul_f32_e32 v3, 0xbfb8aa3b, v9
	v_exp_f32_e32 v2, v2
	v_exp_f32_e32 v3, v3
	v_lshl_add_u64 v[14:15], v[18:19], 0, v[114:115]
	v_add_f32_e32 v2, 1.0, v2
	v_add_f32_e32 v3, 1.0, v3
	v_rcp_f32_e32 v2, v2
	v_rcp_f32_e32 v3, v3
	s_nop 0
	v_pk_mul_f32 v[2:3], v[8:9], v[2:3]
	s_nop 0
	v_pk_mul_f32 v[8:9], v[2:3], v[4:5]
	v_cvt_pk_bf16_f32 v2, v10, v11
	v_cvt_pk_bf16_f32 v3, v12, v13
	v_cvt_pk_bf16_f32 v4, v6, v7
	v_cvt_pk_bf16_f32 v5, v8, v9
	global_store_dwordx4 v[14:15], v[2:5], off sc1
	s_cbranch_vccz .LBB0_95
	s_waitcnt vmcnt(0)
	s_cmpk_gt_u32 s3, 0xff
	s_cbranch_scc1 .LBB0_102
	s_barrier

.LBB0_841:
	s_add_i32 vcc_lo, s71, 2
	s_add_u32 s16, s42, 0x80
	s_addc_u32 s17, s43, 0
	s_add_i32 s84, 0, 0x10000
	v_add_u32_e32 v156, s84, v145
	ds_read_b128 v[140:143], v156
	ds_read_b128 v[148:151], v156 offset:1024
	ds_read_b128 v[152:155], v156 offset:2048
	ds_read_b128 v[156:159], v156 offset:3072
	s_cmp_eq_u32 s12, s71
	s_cselect_b32 s75, s73, s17
	s_cselect_b32 s74, s72, s16
	s_cselect_b32 s77, s45, s15
	s_cselect_b32 s76, s44, s14
	v_lshl_add_u64 v[168:169], s[42:43], 0, v[136:137]
	s_add_i32 m0, s91, 0xc000
	ds_read_b128 v[160:163], v147
	ds_read_b128 v[164:167], v147 offset:1024
	ds_read_b128 v[176:179], v147 offset:2048
	ds_read_b128 v[180:183], v147 offset:3072
	ds_read_b128 v[184:187], v147 offset:4096
	ds_read_b128 v[188:191], v147 offset:5120
	ds_read_b128 v[192:195], v147 offset:6144
	ds_read_b128 v[196:199], v147 offset:7168
	global_load_lds_dwordx4 v[168:169], off
	v_lshl_add_u64 v[168:169], s[42:43], 0, v[138:139]
	s_add_i32 m0, s91, 0xe000
	s_nop 0
	global_load_lds_dwordx4 v[168:169], off
	s_waitcnt lgkmcnt(8)
	s_barrier
	s_waitcnt lgkmcnt(0)
	s_setprio 1
	s_waitcnt lgkmcnt(0)
	v_mfma_f32_16x16x32_bf16 v[126:129], v[140:143], v[160:163], v[126:129]
	v_mfma_f32_16x16x32_bf16 v[122:125], v[152:155], v[160:163], v[122:125]
	v_mfma_f32_16x16x32_bf16 v[114:117], v[140:143], v[176:179], v[114:117]
	v_mfma_f32_16x16x32_bf16 v[106:109], v[152:155], v[176:179], v[106:109]
	v_mfma_f32_16x16x32_bf16 v[98:101], v[140:143], v[184:187], v[98:101]
	v_mfma_f32_16x16x32_bf16 v[90:93], v[152:155], v[184:187], v[90:93]
	v_mfma_f32_16x16x32_bf16 v[82:85], v[140:143], v[192:195], v[82:85]
	v_mfma_f32_16x16x32_bf16 v[74:77], v[152:155], v[192:195], v[74:77]
	v_mfma_f32_16x16x32_bf16 v[126:129], v[148:151], v[164:167], v[126:129]
	v_mfma_f32_16x16x32_bf16 v[122:125], v[156:159], v[164:167], v[122:125]
	v_mfma_f32_16x16x32_bf16 v[114:117], v[148:151], v[180:183], v[114:117]
	v_mfma_f32_16x16x32_bf16 v[106:109], v[156:159], v[180:183], v[106:109]
	v_mfma_f32_16x16x32_bf16 v[98:101], v[148:151], v[188:191], v[98:101]
	v_mfma_f32_16x16x32_bf16 v[90:93], v[156:159], v[188:191], v[90:93]
	v_mfma_f32_16x16x32_bf16 v[82:85], v[148:151], v[196:199], v[82:85]
	v_mfma_f32_16x16x32_bf16 v[74:77], v[156:159], v[196:199], v[74:77]
	s_setprio 0
	s_barrier
	s_add_i32 s16, 0, 0x14000
	v_add_u32_e32 v168, s16, v145
	s_add_i32 s17, s84, s87
	ds_read_b128 v[228:231], v168
	ds_read_b128 v[232:235], v168 offset:1024
	ds_read_b128 v[236:239], v168 offset:2048
	ds_read_b128 v[240:243], v168 offset:3072
	v_lshl_add_u64 v[168:169], s[76:77], 0, v[0:1]
	s_mov_b32 m0, s17
	v_lshl_add_u64 v[200:201], s[76:77], 0, v[134:135]
	global_load_lds_dwordx4 v[168:169], off
	s_add_i32 m0, s17, 0x2000
	s_nop 0
	global_load_lds_dwordx4 v[200:201], off
	s_barrier
	s_waitcnt lgkmcnt(0)
	s_setprio 1
	s_waitcnt lgkmcnt(0)
	v_mfma_f32_16x16x32_bf16 v[118:121], v[228:231], v[160:163], v[118:121]
	v_mfma_f32_16x16x32_bf16 v[110:113], v[236:239], v[160:163], v[110:113]
	v_mfma_f32_16x16x32_bf16 v[102:105], v[228:231], v[176:179], v[102:105]
	v_mfma_f32_16x16x32_bf16 v[94:97], v[236:239], v[176:179], v[94:97]
	v_mfma_f32_16x16x32_bf16 v[86:89], v[228:231], v[184:187], v[86:89]
	v_mfma_f32_16x16x32_bf16 v[78:81], v[236:239], v[184:187], v[78:81]
	v_mfma_f32_16x16x32_bf16 v[70:73], v[228:231], v[192:195], v[70:73]
	v_mfma_f32_16x16x32_bf16 v[66:69], v[236:239], v[192:195], v[66:69]
	v_mfma_f32_16x16x32_bf16 v[118:121], v[232:235], v[164:167], v[118:121]
	v_mfma_f32_16x16x32_bf16 v[110:113], v[240:243], v[164:167], v[110:113]
	v_mfma_f32_16x16x32_bf16 v[102:105], v[232:235], v[180:183], v[102:105]
	v_mfma_f32_16x16x32_bf16 v[94:97], v[240:243], v[180:183], v[94:97]
	v_mfma_f32_16x16x32_bf16 v[86:89], v[232:235], v[188:191], v[86:89]
	v_mfma_f32_16x16x32_bf16 v[78:81], v[240:243], v[188:191], v[78:81]
	v_mfma_f32_16x16x32_bf16 v[70:73], v[232:235], v[196:199], v[70:73]
	v_mfma_f32_16x16x32_bf16 v[66:69], v[240:243], v[196:199], v[66:69]
	s_setprio 0
	s_mov_b32 m0, s91
	v_lshl_add_u64 v[244:245], s[74:75], 0, v[130:131]
	s_barrier
	ds_read_b128 v[160:163], v147 offset:16384
	ds_read_b128 v[164:167], v147 offset:17408
	ds_read_b128 v[176:179], v147 offset:18432
	ds_read_b128 v[180:183], v147 offset:19456
	ds_read_b128 v[184:187], v147 offset:20480
	ds_read_b128 v[188:191], v147 offset:21504
	ds_read_b128 v[192:195], v147 offset:22528
	ds_read_b128 v[196:199], v147 offset:23552
	global_load_lds_dwordx4 v[244:245], off
	v_lshl_add_u64 v[246:247], s[74:75], 0, v[132:133]
	s_mov_b32 m0, s92
	s_nop 0
	global_load_lds_dwordx4 v[246:247], off
	s_barrier
	s_waitcnt lgkmcnt(0)
	s_setprio 1
	s_waitcnt lgkmcnt(0)
	v_mfma_f32_16x16x32_bf16 v[62:65], v[140:143], v[160:163], v[62:65]
	v_mfma_f32_16x16x32_bf16 v[58:61], v[152:155], v[160:163], v[58:61]
	v_mfma_f32_16x16x32_bf16 v[54:57], v[140:143], v[176:179], v[54:57]
	v_mfma_f32_16x16x32_bf16 v[46:49], v[152:155], v[176:179], v[46:49]
	v_mfma_f32_16x16x32_bf16 v[38:41], v[140:143], v[184:187], v[38:41]
	v_mfma_f32_16x16x32_bf16 v[30:33], v[152:155], v[184:187], v[30:33]
	v_mfma_f32_16x16x32_bf16 v[22:25], v[140:143], v[192:195], v[22:25]
	v_mfma_f32_16x16x32_bf16 v[14:17], v[152:155], v[192:195], v[14:17]
	v_mfma_f32_16x16x32_bf16 v[62:65], v[148:151], v[164:167], v[62:65]
	v_mfma_f32_16x16x32_bf16 v[58:61], v[156:159], v[164:167], v[58:61]
	v_mfma_f32_16x16x32_bf16 v[54:57], v[148:151], v[180:183], v[54:57]
	v_mfma_f32_16x16x32_bf16 v[46:49], v[156:159], v[180:183], v[46:49]
	v_mfma_f32_16x16x32_bf16 v[38:41], v[148:151], v[188:191], v[38:41]
	v_mfma_f32_16x16x32_bf16 v[30:33], v[156:159], v[188:191], v[30:33]
	v_mfma_f32_16x16x32_bf16 v[22:25], v[148:151], v[196:199], v[22:25]
	v_mfma_f32_16x16x32_bf16 v[14:17], v[156:159], v[196:199], v[14:17]
	s_setprio 0
	s_barrier
	s_add_u32 s76, s76, s64
	s_addc_u32 s77, s77, 0
	s_add_i32 s16, s16, s87
	v_lshl_add_u64 v[248:249], s[76:77], 0, v[0:1]
	s_mov_b32 m0, s16
	v_lshl_add_u64 v[250:251], s[76:77], 0, v[134:135]
	global_load_lds_dwordx4 v[248:249], off
	s_add_i32 m0, s16, 0x2000
	s_nop 0
	global_load_lds_dwordx4 v[250:251], off
	s_waitcnt vmcnt(6)
	s_barrier
	s_setprio 1
	v_mfma_f32_16x16x32_bf16 v[50:53], v[228:231], v[160:163], v[50:53]
	v_mfma_f32_16x16x32_bf16 v[42:45], v[236:239], v[160:163], v[42:45]
	v_mfma_f32_16x16x32_bf16 v[34:37], v[228:231], v[176:179], v[34:37]
	v_mfma_f32_16x16x32_bf16 v[26:29], v[236:239], v[176:179], v[26:29]
	v_mfma_f32_16x16x32_bf16 v[18:21], v[228:231], v[184:187], v[18:21]
	v_mfma_f32_16x16x32_bf16 v[10:13], v[236:239], v[184:187], v[10:13]
	v_mfma_f32_16x16x32_bf16 v[6:9], v[228:231], v[192:195], v[6:9]
	v_mfma_f32_16x16x32_bf16 v[2:5], v[236:239], v[192:195], v[2:5]
	v_mfma_f32_16x16x32_bf16 v[50:53], v[232:235], v[164:167], v[50:53]
	v_mfma_f32_16x16x32_bf16 v[42:45], v[240:243], v[164:167], v[42:45]
	v_mfma_f32_16x16x32_bf16 v[34:37], v[232:235], v[180:183], v[34:37]
	v_mfma_f32_16x16x32_bf16 v[26:29], v[240:243], v[180:183], v[26:29]
	v_mfma_f32_16x16x32_bf16 v[18:21], v[232:235], v[188:191], v[18:21]
	v_mfma_f32_16x16x32_bf16 v[10:13], v[240:243], v[188:191], v[10:13]
	v_mfma_f32_16x16x32_bf16 v[6:9], v[232:235], v[196:199], v[6:9]
	v_mfma_f32_16x16x32_bf16 v[2:5], v[240:243], v[196:199], v[2:5]
	s_setprio 0
	s_add_i32 s16, 0, 0x18000
	v_add_u32_e32 v156, s16, v145
	s_barrier
	ds_read_b128 v[140:143], v156
	ds_read_b128 v[148:151], v156 offset:1024
	ds_read_b128 v[152:155], v156 offset:2048
	ds_read_b128 v[156:159], v156 offset:3072
	s_add_u32 s74, s74, s64
	s_addc_u32 s75, s75, 0
	s_mov_b32 m0, s93
	v_lshl_add_u64 v[228:229], s[74:75], 0, v[130:131]
	ds_read_b128 v[160:163], v147 offset:32768
	ds_read_b128 v[164:167], v147 offset:33792
	ds_read_b128 v[176:179], v147 offset:34816
	ds_read_b128 v[180:183], v147 offset:35840
	ds_read_b128 v[184:187], v147 offset:36864
	ds_read_b128 v[188:191], v147 offset:37888
	ds_read_b128 v[192:195], v147 offset:38912
	ds_read_b128 v[196:199], v147 offset:39936
	global_load_lds_dwordx4 v[228:229], off
	v_lshl_add_u64 v[228:229], s[74:75], 0, v[132:133]
	s_mov_b32 m0, s94
	s_nop 0
	global_load_lds_dwordx4 v[228:229], off
	s_waitcnt lgkmcnt(8)
	s_barrier
	s_waitcnt lgkmcnt(0)
	s_setprio 1
	s_waitcnt lgkmcnt(0)
	v_mfma_f32_16x16x32_bf16 v[126:129], v[140:143], v[160:163], v[126:129]
	v_mfma_f32_16x16x32_bf16 v[122:125], v[152:155], v[160:163], v[122:125]
	v_mfma_f32_16x16x32_bf16 v[114:117], v[140:143], v[176:179], v[114:117]
	v_mfma_f32_16x16x32_bf16 v[106:109], v[152:155], v[176:179], v[106:109]
	v_mfma_f32_16x16x32_bf16 v[98:101], v[140:143], v[184:187], v[98:101]
	v_mfma_f32_16x16x32_bf16 v[90:93], v[152:155], v[184:187], v[90:93]
	v_mfma_f32_16x16x32_bf16 v[82:85], v[140:143], v[192:195], v[82:85]
	v_mfma_f32_16x16x32_bf16 v[74:77], v[152:155], v[192:195], v[74:77]
	v_mfma_f32_16x16x32_bf16 v[126:129], v[148:151], v[164:167], v[126:129]
	v_mfma_f32_16x16x32_bf16 v[122:125], v[156:159], v[164:167], v[122:125]
	v_mfma_f32_16x16x32_bf16 v[114:117], v[148:151], v[180:183], v[114:117]
	v_mfma_f32_16x16x32_bf16 v[106:109], v[156:159], v[180:183], v[106:109]
	v_mfma_f32_16x16x32_bf16 v[98:101], v[148:151], v[188:191], v[98:101]
	v_mfma_f32_16x16x32_bf16 v[90:93], v[156:159], v[188:191], v[90:93]
	v_mfma_f32_16x16x32_bf16 v[82:85], v[148:151], v[196:199], v[82:85]
	v_mfma_f32_16x16x32_bf16 v[74:77], v[156:159], v[196:199], v[74:77]
	s_setprio 0
	s_barrier
	s_add_i32 s17, 0, 0x1c000
	s_add_i32 s16, s16, s87
	v_add_u32_e32 v175, s17, v145
	v_lshl_add_u64 v[168:169], v[168:169], 0, s[34:35]
	s_mov_b32 m0, s16
	ds_read_b128 v[228:231], v175
	ds_read_b128 v[232:235], v175 offset:1024
	ds_read_b128 v[236:239], v175 offset:2048
	ds_read_b128 v[240:243], v175 offset:3072
	global_load_lds_dwordx4 v[168:169], off
	v_lshl_add_u64 v[168:169], v[200:201], 0, s[34:35]
	s_add_i32 m0, s16, 0x2000
	s_nop 0
	global_load_lds_dwordx4 v[168:169], off
	s_barrier
	s_waitcnt lgkmcnt(0)
	s_setprio 1
	s_waitcnt lgkmcnt(0)
	v_mfma_f32_16x16x32_bf16 v[118:121], v[228:231], v[160:163], v[118:121]
	v_mfma_f32_16x16x32_bf16 v[110:113], v[236:239], v[160:163], v[110:113]
	v_mfma_f32_16x16x32_bf16 v[102:105], v[228:231], v[176:179], v[102:105]
	v_mfma_f32_16x16x32_bf16 v[94:97], v[236:239], v[176:179], v[94:97]
	v_mfma_f32_16x16x32_bf16 v[86:89], v[228:231], v[184:187], v[86:89]
	v_mfma_f32_16x16x32_bf16 v[78:81], v[236:239], v[184:187], v[78:81]
	v_mfma_f32_16x16x32_bf16 v[70:73], v[228:231], v[192:195], v[70:73]
	v_mfma_f32_16x16x32_bf16 v[66:69], v[236:239], v[192:195], v[66:69]
	v_mfma_f32_16x16x32_bf16 v[118:121], v[232:235], v[164:167], v[118:121]
	v_mfma_f32_16x16x32_bf16 v[110:113], v[240:243], v[164:167], v[110:113]
	v_mfma_f32_16x16x32_bf16 v[102:105], v[232:235], v[180:183], v[102:105]
	v_mfma_f32_16x16x32_bf16 v[94:97], v[240:243], v[180:183], v[94:97]
	v_mfma_f32_16x16x32_bf16 v[86:89], v[232:235], v[188:191], v[86:89]
	v_mfma_f32_16x16x32_bf16 v[78:81], v[240:243], v[188:191], v[78:81]
	v_mfma_f32_16x16x32_bf16 v[70:73], v[232:235], v[196:199], v[70:73]
	v_mfma_f32_16x16x32_bf16 v[66:69], v[240:243], v[196:199], v[66:69]
	s_setprio 0
	s_mov_b32 m0, s96
	v_lshl_add_u64 v[168:169], v[244:245], 0, s[34:35]
	s_barrier
	ds_read_b128 v[160:163], v147 offset:49152
	ds_read_b128 v[164:167], v147 offset:50176
	ds_read_b128 v[176:179], v147 offset:51200
	ds_read_b128 v[180:183], v147 offset:52224
	ds_read_b128 v[184:187], v147 offset:53248
	ds_read_b128 v[188:191], v147 offset:54272
	ds_read_b128 v[192:195], v147 offset:55296
	ds_read_b128 v[196:199], v147 offset:56320
	global_load_lds_dwordx4 v[168:169], off
	v_lshl_add_u64 v[168:169], v[246:247], 0, s[34:35]
	s_mov_b32 m0, s97
	s_nop 0
	global_load_lds_dwordx4 v[168:169], off
	s_barrier
	s_waitcnt lgkmcnt(0)
	s_setprio 1
	s_waitcnt lgkmcnt(0)
	v_mfma_f32_16x16x32_bf16 v[62:65], v[140:143], v[160:163], v[62:65]
	v_mfma_f32_16x16x32_bf16 v[58:61], v[152:155], v[160:163], v[58:61]
	v_mfma_f32_16x16x32_bf16 v[54:57], v[140:143], v[176:179], v[54:57]
	v_mfma_f32_16x16x32_bf16 v[46:49], v[152:155], v[176:179], v[46:49]
	v_mfma_f32_16x16x32_bf16 v[38:41], v[140:143], v[184:187], v[38:41]
	v_mfma_f32_16x16x32_bf16 v[30:33], v[152:155], v[184:187], v[30:33]
	v_mfma_f32_16x16x32_bf16 v[22:25], v[140:143], v[192:195], v[22:25]
	v_mfma_f32_16x16x32_bf16 v[14:17], v[152:155], v[192:195], v[14:17]
	v_mfma_f32_16x16x32_bf16 v[62:65], v[148:151], v[164:167], v[62:65]
	v_mfma_f32_16x16x32_bf16 v[58:61], v[156:159], v[164:167], v[58:61]
	v_mfma_f32_16x16x32_bf16 v[54:57], v[148:151], v[180:183], v[54:57]
	v_mfma_f32_16x16x32_bf16 v[46:49], v[156:159], v[180:183], v[46:49]
	v_mfma_f32_16x16x32_bf16 v[38:41], v[148:151], v[188:191], v[38:41]
	v_mfma_f32_16x16x32_bf16 v[30:33], v[156:159], v[188:191], v[30:33]
	v_mfma_f32_16x16x32_bf16 v[22:25], v[148:151], v[196:199], v[22:25]
	v_mfma_f32_16x16x32_bf16 v[14:17], v[156:159], v[196:199], v[14:17]
	s_setprio 0
	s_barrier
	s_add_i32 s16, s17, s87
	v_lshl_add_u64 v[140:141], v[248:249], 0, s[34:35]
	s_mov_b32 m0, s16
	s_nop 0
	global_load_lds_dwordx4 v[140:141], off
	v_lshl_add_u64 v[140:141], v[250:251], 0, s[34:35]
	s_add_i32 m0, s16, 0x2000
	s_nop 0
	global_load_lds_dwordx4 v[140:141], off
	s_waitcnt vmcnt(6)
	s_barrier
	s_setprio 1
	v_mfma_f32_16x16x32_bf16 v[50:53], v[228:231], v[160:163], v[50:53]
	v_mfma_f32_16x16x32_bf16 v[42:45], v[236:239], v[160:163], v[42:45]
	v_mfma_f32_16x16x32_bf16 v[34:37], v[228:231], v[176:179], v[34:37]
	v_mfma_f32_16x16x32_bf16 v[26:29], v[236:239], v[176:179], v[26:29]
	v_mfma_f32_16x16x32_bf16 v[18:21], v[228:231], v[184:187], v[18:21]
	v_mfma_f32_16x16x32_bf16 v[10:13], v[236:239], v[184:187], v[10:13]
	v_mfma_f32_16x16x32_bf16 v[6:9], v[228:231], v[192:195], v[6:9]
	v_mfma_f32_16x16x32_bf16 v[2:5], v[236:239], v[192:195], v[2:5]
	v_mfma_f32_16x16x32_bf16 v[50:53], v[232:235], v[164:167], v[50:53]
	v_mfma_f32_16x16x32_bf16 v[42:45], v[240:243], v[164:167], v[42:45]
	v_mfma_f32_16x16x32_bf16 v[34:37], v[232:235], v[180:183], v[34:37]
	v_mfma_f32_16x16x32_bf16 v[26:29], v[240:243], v[180:183], v[26:29]
	v_mfma_f32_16x16x32_bf16 v[18:21], v[232:235], v[188:191], v[18:21]
	v_mfma_f32_16x16x32_bf16 v[10:13], v[240:243], v[188:191], v[10:13]
	v_mfma_f32_16x16x32_bf16 v[6:9], v[232:235], v[196:199], v[6:9]
	v_mfma_f32_16x16x32_bf16 v[2:5], v[240:243], v[196:199], v[2:5]
	s_setprio 0
	s_add_u32 s42, s42, 0x100
	s_addc_u32 s43, s43, 0
	s_add_u32 s14, s14, 0x100
	s_addc_u32 s15, s15, 0
	s_cmp_ge_u32 vcc_lo, s18
	s_mov_b32 s71, vcc_lo
	s_barrier
	s_cbranch_scc0 .LBB0_841
	s_mul_hi_i32 s15, s60, s95
	s_mul_i32 s14, s60, s95
	s_lshl_b64 s[14:15], s[14:15], 1
	v_lshl_add_u32 v148, s83, 8, v144
	s_add_u32 s74, s58, s14
	v_lshl_or_b32 v140, s82, 8, v146
	s_addc_u32 s75, s59, s15
	v_mad_i64_i32 v[142:143], s[14:15], v148, s21, 0
	v_lshl_add_u64 v[142:143], v[142:143], 1, s[74:75]
	v_cmp_gt_i32_e32 vcc, s19, v140
	v_ashrrev_i32_e32 v141, 31, v140
	s_and_saveexec_b64 s[14:15], vcc
	s_cbranch_execz .LBB0_844
	v_cvt_pk_bf16_f32 v126, v126, v127
	v_cvt_pk_bf16_f32 v127, v128, v129
	v_cvt_pk_bf16_f32 v128, v122, v123
	v_cvt_pk_bf16_f32 v129, v124, v125
	v_lshl_add_u64 v[122:123], v[140:141], 1, v[142:143]
	global_store_dwordx4 v[122:123], v[126:129], off sc1
.LBB0_844:
	s_or_b64 exec, exec, s[14:15]
	v_or_b32_e32 v122, 0x80, v140
	v_cmp_gt_i32_e64 s[42:43], s19, v122
	s_and_saveexec_b64 s[14:15], s[42:43]
	s_cbranch_execz .LBB0_846
	v_cvt_pk_bf16_f32 v118, v118, v119
	v_cvt_pk_bf16_f32 v119, v120, v121
	v_cvt_pk_bf16_f32 v120, v110, v111
	v_cvt_pk_bf16_f32 v121, v112, v113
	v_lshl_add_u64 v[110:111], v[140:141], 1, v[142:143]
	global_store_dwordx4 v[110:111], v[118:121], off offset:256 sc1
.LBB0_846:
	s_or_b64 exec, exec, s[14:15]
	v_or_b32_e32 v110, 16, v148
	v_mad_i64_i32 v[110:111], s[14:15], v110, s21, 0
	v_lshl_add_u64 v[110:111], v[110:111], 1, s[74:75]
	s_and_saveexec_b64 s[14:15], vcc
	s_cbranch_execz .LBB0_848
	v_cvt_pk_bf16_f32 v112, v114, v115
	v_cvt_pk_bf16_f32 v113, v116, v117
	v_cvt_pk_bf16_f32 v114, v106, v107
	v_cvt_pk_bf16_f32 v115, v108, v109
	v_lshl_add_u64 v[106:107], v[140:141], 1, v[110:111]
	global_store_dwordx4 v[106:107], v[112:115], off sc1
.LBB0_848:
	s_or_b64 exec, exec, s[14:15]
	s_and_saveexec_b64 s[14:15], s[42:43]
	s_cbranch_execz .LBB0_850
	v_cvt_pk_bf16_f32 v102, v102, v103
	v_cvt_pk_bf16_f32 v103, v104, v105
	v_cvt_pk_bf16_f32 v104, v94, v95
	v_cvt_pk_bf16_f32 v105, v96, v97
	v_lshl_add_u64 v[94:95], v[140:141], 1, v[110:111]
	global_store_dwordx4 v[94:95], v[102:105], off offset:256 sc1
.LBB0_850:
	s_or_b64 exec, exec, s[14:15]
	v_or_b32_e32 v94, 32, v148
	v_mad_i64_i32 v[94:95], s[14:15], v94, s21, 0
	v_lshl_add_u64 v[94:95], v[94:95], 1, s[74:75]
	s_and_saveexec_b64 s[14:15], vcc
	s_cbranch_execz .LBB0_852
	v_cvt_pk_bf16_f32 v96, v98, v99
	v_cvt_pk_bf16_f32 v97, v100, v101
	v_cvt_pk_bf16_f32 v98, v90, v91
	v_cvt_pk_bf16_f32 v99, v92, v93
	v_lshl_add_u64 v[90:91], v[140:141], 1, v[94:95]
	global_store_dwordx4 v[90:91], v[96:99], off sc1
.LBB0_852:
	s_or_b64 exec, exec, s[14:15]
	s_and_saveexec_b64 s[14:15], s[42:43]
	s_cbranch_execz .LBB0_854
	v_cvt_pk_bf16_f32 v86, v86, v87
	v_cvt_pk_bf16_f32 v87, v88, v89
	v_cvt_pk_bf16_f32 v88, v78, v79
	v_cvt_pk_bf16_f32 v89, v80, v81
	v_lshl_add_u64 v[78:79], v[140:141], 1, v[94:95]
	global_store_dwordx4 v[78:79], v[86:89], off offset:256 sc1
.LBB0_854:
	s_or_b64 exec, exec, s[14:15]
	v_or_b32_e32 v78, 48, v148
	v_mad_i64_i32 v[78:79], s[14:15], v78, s21, 0
	v_lshl_add_u64 v[78:79], v[78:79], 1, s[74:75]
	s_and_saveexec_b64 s[14:15], vcc
	s_cbranch_execz .LBB0_856
	v_cvt_pk_bf16_f32 v80, v82, v83
	v_cvt_pk_bf16_f32 v81, v84, v85
	v_cvt_pk_bf16_f32 v82, v74, v75
	v_cvt_pk_bf16_f32 v83, v76, v77
	v_lshl_add_u64 v[74:75], v[140:141], 1, v[78:79]
	global_store_dwordx4 v[74:75], v[80:83], off sc1
.LBB0_856:
	s_or_b64 exec, exec, s[14:15]
	s_and_saveexec_b64 s[14:15], s[42:43]
	s_cbranch_execz .LBB0_858
	v_cvt_pk_bf16_f32 v70, v70, v71
	v_cvt_pk_bf16_f32 v71, v72, v73
	v_cvt_pk_bf16_f32 v72, v66, v67
	v_cvt_pk_bf16_f32 v73, v68, v69
	v_lshl_add_u64 v[66:67], v[140:141], 1, v[78:79]
	global_store_dwordx4 v[66:67], v[70:73], off offset:256 sc1
.LBB0_858:
	s_or_b64 exec, exec, s[14:15]
	v_add_u32_e32 v66, 0x80, v148
	v_mad_i64_i32 v[66:67], s[14:15], v66, s21, 0
	v_lshl_add_u64 v[66:67], v[66:67], 1, s[74:75]
	s_and_saveexec_b64 s[14:15], vcc
	s_cbranch_execz .LBB0_860
	v_cvt_pk_bf16_f32 v62, v62, v63
	v_cvt_pk_bf16_f32 v63, v64, v65
	v_cvt_pk_bf16_f32 v64, v58, v59
	v_cvt_pk_bf16_f32 v65, v60, v61
	v_lshl_add_u64 v[58:59], v[140:141], 1, v[66:67]
	global_store_dwordx4 v[58:59], v[62:65], off sc1
.LBB0_860:
	s_or_b64 exec, exec, s[14:15]
	s_and_saveexec_b64 s[14:15], s[42:43]
	s_cbranch_execz .LBB0_862
	v_cvt_pk_bf16_f32 v50, v50, v51
	v_cvt_pk_bf16_f32 v51, v52, v53
	v_cvt_pk_bf16_f32 v52, v42, v43
	v_cvt_pk_bf16_f32 v53, v44, v45
	v_lshl_add_u64 v[42:43], v[140:141], 1, v[66:67]
	global_store_dwordx4 v[42:43], v[50:53], off offset:256 sc1
.LBB0_862:
	s_or_b64 exec, exec, s[14:15]
	v_add_u32_e32 v42, 0x90, v148
	v_mad_i64_i32 v[42:43], s[14:15], v42, s21, 0
	v_lshl_add_u64 v[42:43], v[42:43], 1, s[74:75]
	s_and_saveexec_b64 s[14:15], vcc
	s_cbranch_execz .LBB0_864
	v_cvt_pk_bf16_f32 v44, v54, v55
	v_cvt_pk_bf16_f32 v45, v56, v57
	v_cvt_pk_bf16_f32 v46, v46, v47
	v_cvt_pk_bf16_f32 v47, v48, v49
	v_lshl_add_u64 v[48:49], v[140:141], 1, v[42:43]
	global_store_dwordx4 v[48:49], v[44:47], off sc1
.LBB0_864:
	s_or_b64 exec, exec, s[14:15]
	s_and_saveexec_b64 s[14:15], s[42:43]
	s_cbranch_execz .LBB0_866
	v_cvt_pk_bf16_f32 v34, v34, v35
	v_cvt_pk_bf16_f32 v35, v36, v37
	v_cvt_pk_bf16_f32 v36, v26, v27
	v_cvt_pk_bf16_f32 v37, v28, v29
	v_lshl_add_u64 v[26:27], v[140:141], 1, v[42:43]
	global_store_dwordx4 v[26:27], v[34:37], off offset:256 sc1
.LBB0_866:
	s_or_b64 exec, exec, s[14:15]
	v_add_u32_e32 v26, 0xa0, v148
	v_mad_i64_i32 v[26:27], s[14:15], v26, s21, 0
	v_lshl_add_u64 v[26:27], v[26:27], 1, s[74:75]
	s_and_saveexec_b64 s[14:15], vcc
	s_cbranch_execz .LBB0_868
	v_cvt_pk_bf16_f32 v28, v38, v39
	v_cvt_pk_bf16_f32 v29, v40, v41
	v_cvt_pk_bf16_f32 v30, v30, v31
	v_cvt_pk_bf16_f32 v31, v32, v33
	v_lshl_add_u64 v[32:33], v[140:141], 1, v[26:27]
	global_store_dwordx4 v[32:33], v[28:31], off sc1
.LBB0_868:
	s_or_b64 exec, exec, s[14:15]
	s_and_saveexec_b64 s[14:15], s[42:43]
	s_cbranch_execz .LBB0_870
	v_cvt_pk_bf16_f32 v18, v18, v19
	v_cvt_pk_bf16_f32 v19, v20, v21
	v_cvt_pk_bf16_f32 v20, v10, v11
	v_cvt_pk_bf16_f32 v21, v12, v13
	v_lshl_add_u64 v[10:11], v[140:141], 1, v[26:27]
	global_store_dwordx4 v[10:11], v[18:21], off offset:256 sc1
.LBB0_870:
	s_or_b64 exec, exec, s[14:15]
	v_add_u32_e32 v10, 0xb0, v148
	v_mad_i64_i32 v[10:11], s[14:15], v10, s21, 0
	v_lshl_add_u64 v[10:11], v[10:11], 1, s[74:75]
	s_and_saveexec_b64 s[14:15], vcc
	s_cbranch_execz .LBB0_872
	v_cvt_pk_bf16_f32 v12, v22, v23
	v_cvt_pk_bf16_f32 v13, v24, v25
	v_cvt_pk_bf16_f32 v14, v14, v15
	v_cvt_pk_bf16_f32 v15, v16, v17
	v_lshl_add_u64 v[16:17], v[140:141], 1, v[10:11]
	global_store_dwordx4 v[16:17], v[12:15], off sc1
.LBB0_872:
	s_or_b64 exec, exec, s[14:15]
	s_and_saveexec_b64 s[14:15], s[42:43]
	s_cbranch_execz .LBB0_826
	v_cvt_pk_bf16_f32 v6, v6, v7
	v_cvt_pk_bf16_f32 v7, v8, v9
	v_cvt_pk_bf16_f32 v8, v2, v3
	v_cvt_pk_bf16_f32 v9, v4, v5
	v_lshl_add_u64 v[2:3], v[140:141], 1, v[10:11]
	global_store_dwordx4 v[2:3], v[6:9], off offset:256 sc1
	s_branch .LBB0_826

.LBB0_1017:
	s_or_b64 exec, exec, s[40:41]
	v_pk_mul_f32 v[92:93], v[52:53], v[178:179] op_sel:[0,1]
	v_lshl_add_u64 v[90:91], v[90:91], 2, v[152:153]
	v_pk_mul_f32 v[94:95], v[68:69], v[92:93]
	v_pk_mul_f32 v[92:93], v[66:67], v[88:89]
	v_pk_mul_f32 v[88:89], v[56:57], v[178:179] op_sel:[0,1]
	v_pk_mul_f32 v[86:87], v[70:71], v[86:87]
	v_pk_mul_f32 v[88:89], v[72:73], v[88:89]
	global_store_dwordx4 v[90:91], v[86:89], off offset:1024 sc1
	v_pk_mul_f32 v[84:85], v[74:75], v[84:85]
	v_pk_mul_f32 v[82:83], v[78:79], v[82:83]
	v_pk_mul_f32 v[86:87], v[60:61], v[178:179] op_sel:[0,1]
	global_store_dwordx4 v[90:91], v[92:95], off sc1
	v_pk_mul_f32 v[86:87], v[76:77], v[86:87]
	global_store_dwordx4 v[90:91], v[84:87], off offset:2048 sc1
	s_nop 1
	v_pk_mul_f32 v[84:85], v[64:65], v[178:179] op_sel:[0,1]
	s_nop 0
	v_pk_mul_f32 v[84:85], v[80:81], v[84:85]
	global_store_dwordx4 v[90:91], v[82:85], off offset:3072 sc1

.LBB0_1043:
	s_or_b64 exec, exec, s[52:53]
	s_mov_b64 s[52:53], -1
	s_and_b64 vcc, exec, s[42:43]
	v_pk_mul_f32 v[120:121], v[94:95], v[178:179] op_sel_hi:[1,0]
	v_pk_mul_f32 v[118:119], v[90:91], v[178:179] op_sel_hi:[1,0]
	v_pk_mul_f32 v[116:117], v[86:87], v[178:179] op_sel_hi:[1,0]
	v_pk_mul_f32 v[114:115], v[82:83], v[178:179] op_sel_hi:[1,0]
	s_cbranch_vccnz .LBB0_1046
	v_lshl_add_u64 v[122:123], s[80:81], 0, v[162:163]
	global_store_dwordx4 v[122:123], v[94:97], off sc1
	global_store_dwordx4 v[122:123], v[90:93], off offset:1024 sc1
	global_store_dwordx4 v[122:123], v[86:89], off offset:2048 sc1
	global_store_dwordx4 v[122:123], v[82:85], off offset:3072 sc1
	v_pk_add_f32 v[90:91], v[110:111], 1.0 op_sel_hi:[1,0]
	v_pk_add_f32 v[86:87], v[112:113], 1.0 op_sel_hi:[1,0]
	v_pk_mul_f32 v[82:83], v[96:97], v[178:179] op_sel_hi:[1,0]
	s_mov_b32 s12, 0x1800000
	v_pk_fma_f32 v[82:83], v[86:87], v[82:83], v[28:29]
	v_pk_fma_f32 v[86:87], v[90:91], v[120:121], v[26:27]
	v_pk_add_f32 v[90:91], v[108:109], 1.0 op_sel_hi:[1,0]
	v_cvt_pk_bf16_f32 v86, v86, v87
	v_cvt_pk_bf16_f32 v87, v82, v83
	v_add_co_u32_e32 v82, vcc, s12, v200
	v_pk_add_f32 v[94:95], v[106:107], 1.0 op_sel_hi:[1,0]
	s_nop 0
	v_addc_co_u32_e32 v83, vcc, 0, v201, vcc
	global_store_dwordx2 v[82:83], v[86:87], off
	v_pk_mul_f32 v[86:87], v[92:93], v[178:179] op_sel_hi:[1,0]
	s_nop 0
	v_pk_fma_f32 v[86:87], v[90:91], v[86:87], v[36:37]
	v_pk_fma_f32 v[90:91], v[94:95], v[118:119], v[34:35]
	v_pk_add_f32 v[94:95], v[102:103], 1.0 op_sel_hi:[1,0]
	v_cvt_pk_bf16_f32 v90, v90, v91
	v_cvt_pk_bf16_f32 v91, v86, v87
	global_store_dwordx2 v[82:83], v[90:91], off offset:512
	v_pk_mul_f32 v[86:87], v[88:89], v[178:179] op_sel_hi:[1,0]
	v_pk_add_f32 v[90:91], v[104:105], 1.0 op_sel_hi:[1,0]
	s_nop 0
	v_pk_fma_f32 v[86:87], v[90:91], v[86:87], v[44:45]
	v_pk_fma_f32 v[90:91], v[94:95], v[116:117], v[42:43]
	v_pk_add_f32 v[94:95], v[98:99], 1.0 op_sel_hi:[1,0]
	v_cvt_pk_bf16_f32 v90, v90, v91
	v_cvt_pk_bf16_f32 v91, v86, v87
	global_store_dwordx2 v[82:83], v[90:91], off offset:1024
	v_pk_mul_f32 v[86:87], v[84:85], v[178:179] op_sel_hi:[1,0]
	v_pk_add_f32 v[90:91], v[100:101], 1.0 op_sel_hi:[1,0]
	s_nop 0
	v_pk_fma_f32 v[86:87], v[90:91], v[86:87], v[48:49]
	v_pk_fma_f32 v[90:91], v[94:95], v[114:115], v[46:47]
	s_nop 0
	v_cvt_pk_bf16_f32 v90, v90, v91
	v_cvt_pk_bf16_f32 v91, v86, v87
	global_store_dwordx2 v[82:83], v[90:91], off offset:1536
	s_cbranch_execz .LBB0_1047

.LBB0_1047:
	v_cmp_lt_i32_e32 vcc, s91, v157
	v_mov_b64_e32 v[82:83], v[158:159]
	s_and_saveexec_b64 s[52:53], vcc
	v_mov_b32_e32 v157, v1
	v_lshlrev_b64 v[82:83], 10, v[156:157]
	s_mov_b64 s[12:13], 0x400000
	v_lshl_add_u64 v[82:83], v[82:83], 0, s[12:13]
	s_or_b64 exec, exec, s[52:53]
	v_pk_mul_f32 v[94:95], v[110:111], v[120:121]
	v_lshl_add_u64 v[110:111], v[82:83], 2, v[152:153]
	v_pk_mul_f32 v[82:83], v[92:93], v[178:179] op_sel_hi:[1,0]
	v_pk_mul_f32 v[86:87], v[96:97], v[178:179] op_sel_hi:[1,0]
	v_pk_mul_f32 v[92:93], v[108:109], v[82:83]
	v_pk_mul_f32 v[82:83], v[88:89], v[178:179] op_sel_hi:[1,0]
	v_pk_mul_f32 v[96:97], v[112:113], v[86:87]
	v_pk_mul_f32 v[88:89], v[104:105], v[82:83]
	v_pk_mul_f32 v[82:83], v[84:85], v[178:179] op_sel_hi:[1,0]
	v_pk_mul_f32 v[90:91], v[106:107], v[118:119]
	v_pk_mul_f32 v[86:87], v[102:103], v[116:117]
	v_pk_mul_f32 v[84:85], v[100:101], v[82:83]
	v_pk_mul_f32 v[82:83], v[98:99], v[114:115]
	global_store_dwordx4 v[110:111], v[94:97], off sc1
	global_store_dwordx4 v[110:111], v[90:93], off offset:1024 sc1
	global_store_dwordx4 v[110:111], v[86:89], off offset:2048 sc1
	global_store_dwordx4 v[110:111], v[82:85], off offset:3072 sc1
	s_and_saveexec_b64 s[52:53], s[40:41]
	s_cbranch_execz .LBB0_1018
.LBB0_1050:
	s_mov_b64 s[40:41], -1
	s_and_b64 vcc, exec, s[42:43]
	v_pk_mul_f32 v[88:89], v[50:51], v[178:179] op_sel:[0,1]
	v_pk_mul_f32 v[86:87], v[54:55], v[178:179] op_sel:[0,1]
	v_pk_mul_f32 v[84:85], v[58:59], v[178:179] op_sel:[0,1]
	v_pk_mul_f32 v[82:83], v[62:63], v[178:179] op_sel:[0,1]
	s_cbranch_vccnz .LBB0_1052
	v_ashrrev_i32_e32 v197, 31, v196
	v_lshlrev_b64 v[90:91], 12, v[196:197]
	v_lshl_add_u64 v[90:91], v[148:149], 0, v[90:91]
	v_pk_mul_f32 v[92:93], v[52:53], v[178:179] op_sel:[0,1]
	v_pk_add_f32 v[94:95], v[68:69], 1.0 op_sel_hi:[1,0]
	v_pk_add_f32 v[96:97], v[66:67], 1.0 op_sel_hi:[1,0]
	global_store_dwordx4 v[90:91], v[50:53], off sc1
	global_store_dwordx4 v[90:91], v[54:57], off offset:1024 sc1
	global_store_dwordx4 v[90:91], v[58:61], off offset:2048 sc1
	global_store_dwordx4 v[90:91], v[62:65], off offset:3072 sc1
	v_lshlrev_b64 v[90:91], 11, v[196:197]
	v_pk_fma_f32 v[92:93], v[94:95], v[92:93], v[24:25]
	v_pk_fma_f32 v[94:95], v[96:97], v[88:89], v[22:23]
	v_lshl_add_u64 v[90:91], v[150:151], 0, v[90:91]
	v_cvt_pk_bf16_f32 v94, v94, v95
	v_cvt_pk_bf16_f32 v95, v92, v93
	global_store_dwordx2 v[90:91], v[94:95], off
	v_pk_mul_f32 v[92:93], v[56:57], v[178:179] op_sel:[0,1]
	v_pk_add_f32 v[94:95], v[72:73], 1.0 op_sel_hi:[1,0]
	v_pk_add_f32 v[96:97], v[70:71], 1.0 op_sel_hi:[1,0]
	v_pk_fma_f32 v[92:93], v[94:95], v[92:93], v[20:21]
	v_pk_fma_f32 v[94:95], v[96:97], v[86:87], v[18:19]
	v_pk_add_f32 v[96:97], v[74:75], 1.0 op_sel_hi:[1,0]
	v_cvt_pk_bf16_f32 v94, v94, v95
	v_cvt_pk_bf16_f32 v95, v92, v93
	global_store_dwordx2 v[90:91], v[94:95], off offset:512
	v_pk_mul_f32 v[92:93], v[60:61], v[178:179] op_sel:[0,1]
	v_pk_add_f32 v[94:95], v[76:77], 1.0 op_sel_hi:[1,0]
	s_mov_b64 s[40:41], 0
	v_pk_fma_f32 v[92:93], v[94:95], v[92:93], v[8:9]
	v_pk_fma_f32 v[94:95], v[96:97], v[84:85], v[6:7]
	v_pk_add_f32 v[96:97], v[78:79], 1.0 op_sel_hi:[1,0]
	v_cvt_pk_bf16_f32 v94, v94, v95
	v_cvt_pk_bf16_f32 v95, v92, v93
	global_store_dwordx2 v[90:91], v[94:95], off offset:1024
	v_pk_mul_f32 v[92:93], v[64:65], v[178:179] op_sel:[0,1]
	v_pk_add_f32 v[94:95], v[80:81], 1.0 op_sel_hi:[1,0]
	s_nop 0
	v_pk_fma_f32 v[92:93], v[94:95], v[92:93], v[4:5]
	v_pk_fma_f32 v[94:95], v[96:97], v[82:83], v[2:3]
	s_nop 0
	v_cvt_pk_bf16_f32 v94, v94, v95
	v_cvt_pk_bf16_f32 v95, v92, v93
	global_store_dwordx2 v[90:91], v[94:95], off offset:1536
